# attention S2 schedule variant b (h: exps/cvts first in head; b: rebalanced row-sum adds)
# speedup vs baseline: 1.0111x; 1.0111x over previous
; #define LOADV(dst, ks_) do { _Pragma("unroll") for (int dvb = 0; dvb < 4; ++dvb) { dst[2 * dvb] = vtr(vp + dvb * 4096 + (ks_) * 1024); dst[2 * dvb + 1] = vtr(vp + dvb * 4096 + (ks_) * 1024 + 512); } } while (0)
; #define MF4(src, pfrag) do { _Pragma("unroll") for (int dvb = 0; dvb < 4; ++dvb) { \
;         const bf16x8 vf_ = __builtin_shufflevector(src[2 * dvb], src[2 * dvb + 1], 0, 1, 2, 3, 4, 5, 6, 7); o[dvb] = MFMA32(vf_, pfrag, o[dvb]); } } while (0)
; #define EXPQ(S, lo_, RS, PF) do { _Pragma("unroll") for (int i = lo_; i < lo_ + 8; ++i) { S[i] = ex2(S[i]); RS += S[i]; } \
;               u32x4 w_; w_.x = pk2(S[lo_], S[lo_ + 1]); w_.y = pk2(S[lo_ + 2], S[lo_ + 3]); w_.z = pk2(S[lo_ + 4], S[lo_ + 5]); w_.w = pk2(S[lo_ + 6], S[lo_ + 7]); PF = __builtin_bit_cast(bf16x8, w_); } while (0)
; DI void attn_unit(const Params& p, int bh, int qb, char* lds, float lam, int tid, int lane, int wid, const bool build_tab) {
;     ...
;             float rs0 = 0.f, rs1 = 0.f;
;     ...
;             EXPQ(s0, 0, rs0, pf[0]);
;             LOADV(vb, 1);
;             MF4(va, pf[0]);
;             EXPQ(s0, 8, rs1, pf[1]);
;             LOADV(va, 2);
;             MF4(vb, pf[1]);
;             EXPQ(s1, 0, rs0, pf[2]);
;             LOADV(vb, 3);
;             MF4(va, pf[2]);
;             EXPQ(s1, 8, rs1, pf[3]);
;             MF4(vb, pf[3]);
;             l += rs0 + rs1;
.LBB0_359:
	ds_read_b64_tr_b16 v[242:243], v220 offset:21504
	ds_read_b64_tr_b16 v[244:245], v220 offset:22016
	ds_read_b64_tr_b16 v[246:247], v220 offset:25600
	ds_read_b64_tr_b16 v[248:249], v220 offset:26112
	v_exp_f32_e32 v222, v96
	v_exp_f32_e32 v224, v97
	v_exp_f32_e32 v226, v98
	v_exp_f32_e32 v228, v99
	v_exp_f32_e32 v230, v100
	v_exp_f32_e32 v232, v101
	v_exp_f32_e32 v234, v102
	v_exp_f32_e32 v236, v103
	v_cvt_pk_bf16_f32 v96, v222, v224
	v_cvt_pk_bf16_f32 v97, v226, v228
	v_cvt_pk_bf16_f32 v98, v230, v232
	v_cvt_pk_bf16_f32 v99, v234, v236
	ds_read_b64_tr_b16 v[100:101], v220 offset:17408
	ds_read_b64_tr_b16 v[102:103], v220 offset:17920
	s_waitcnt lgkmcnt(12)
	v_mfma_f32_32x32x16_bf16 v[48:63], v[140:143], v[96:99], v[48:63]
	ds_read_b64_tr_b16 v[250:251], v220 offset:29696
	ds_read_b64_tr_b16 v[252:253], v220 offset:30208
	v_exp_f32_e32 v223, v104
	v_exp_f32_e32 v225, v105
	v_exp_f32_e32 v227, v106
	v_add_f32_e32 v221, v224, v222
	s_waitcnt lgkmcnt(12)
	v_mfma_f32_32x32x16_bf16 v[32:47], v[136:139], v[96:99], v[32:47]
	v_exp_f32_e32 v229, v107
	v_exp_f32_e32 v231, v108
	v_exp_f32_e32 v233, v109
	v_add_f32_e32 v221, v226, v221
	s_waitcnt lgkmcnt(10)
	v_mfma_f32_32x32x16_bf16 v[16:31], v[132:135], v[96:99], v[16:31]
	v_exp_f32_e32 v235, v110
	v_exp_f32_e32 v237, v111
	v_add_f32_e32 v221, v228, v221
	v_add_f32_e32 v221, v230, v221
	ds_read_b64_tr_b16 v[104:105], v220 offset:18432
	ds_read_b64_tr_b16 v[106:107], v220 offset:18944
	ds_read_b64_tr_b16 v[108:109], v220 offset:19456
	ds_read_b64_tr_b16 v[110:111], v220 offset:19968
	s_waitcnt lgkmcnt(12)
	v_mfma_f32_32x32x16_bf16 v[0:15], v[128:131], v[96:99], v[0:15]
	ds_read_b64_tr_b16 v[128:129], v220 offset:26624
	ds_read_b64_tr_b16 v[130:131], v220 offset:27136
	v_cvt_pk_bf16_f32 v96, v223, v225
	v_cvt_pk_bf16_f32 v97, v227, v229
	v_cvt_pk_bf16_f32 v98, v231, v233
	v_cvt_pk_bf16_f32 v99, v235, v237
	v_exp_f32_e32 v140, v84
	v_exp_f32_e32 v142, v85
	s_waitcnt lgkmcnt(8)
	v_mfma_f32_32x32x16_bf16 v[48:63], v[100:103], v[96:99], v[48:63]
	v_exp_f32_e32 v238, v86
	v_exp_f32_e32 v240, v87
	v_add_f32_e32 v221, v232, v221
	ds_read_b64_tr_b16 v[84:85], v220 offset:22528
	ds_read_b64_tr_b16 v[86:87], v220 offset:23040
	v_exp_f32_e32 v136, v82
	s_waitcnt lgkmcnt(14)
	v_mfma_f32_32x32x16_bf16 v[32:47], v[242:245], v[96:99], v[32:47]
	ds_read_b64_tr_b16 v[242:243], v220 offset:23552
	ds_read_b64_tr_b16 v[244:245], v220 offset:24064
	v_exp_f32_e32 v138, v83
	v_exp_f32_e32 v132, v80
	v_exp_f32_e32 v134, v81
	v_add_f32_e32 v221, v234, v221
	s_waitcnt lgkmcnt(14)
	v_mfma_f32_32x32x16_bf16 v[16:31], v[246:249], v[96:99], v[16:31]
	ds_read_b64_tr_b16 v[246:247], v220 offset:27648
	ds_read_b64_tr_b16 v[248:249], v220 offset:28160
	v_cvt_pk_bf16_f32 v80, v132, v134
	v_cvt_pk_bf16_f32 v81, v136, v138
	v_cvt_pk_bf16_f32 v82, v140, v142
	v_cvt_pk_bf16_f32 v83, v238, v240
	v_exp_f32_e32 v133, v88
	v_exp_f32_e32 v135, v89
	s_waitcnt lgkmcnt(12)
	v_mfma_f32_32x32x16_bf16 v[0:15], v[250:253], v[96:99], v[0:15]
	ds_read_b64_tr_b16 v[250:251], v220 offset:31744
	ds_read_b64_tr_b16 v[252:253], v220 offset:32256
	v_exp_f32_e32 v137, v90
	v_exp_f32_e32 v139, v91
	v_add_f32_e32 v221, v236, v221
	ds_read_b64_tr_b16 v[88:89], v220 offset:30720
	ds_read_b64_tr_b16 v[90:91], v220 offset:31232
	v_exp_f32_e32 v141, v92
	s_waitcnt lgkmcnt(14)
	v_mfma_f32_32x32x16_bf16 v[48:63], v[104:107], v[80:83], v[48:63]
	v_exp_f32_e32 v143, v93
	v_exp_f32_e32 v239, v94
	v_exp_f32_e32 v241, v95
	v_add_f32_e32 v221, v132, v221
	s_waitcnt lgkmcnt(8)
	v_mfma_f32_32x32x16_bf16 v[32:47], v[84:87], v[80:83], v[32:47]
	v_add_f32_e32 v93, v225, v223
	v_add_f32_e32 v221, v134, v221
	v_add_f32_e32 v93, v227, v93
	v_add_f32_e32 v221, v136, v221
	s_waitcnt lgkmcnt(10)
	v_mfma_f32_32x32x16_bf16 v[16:31], v[128:131], v[80:83], v[16:31]
	v_add_f32_e32 v93, v229, v93
	v_add_f32_e32 v221, v138, v221
	v_add_f32_e32 v93, v231, v93
	v_add_f32_e32 v221, v140, v221
	v_add_f32_e32 v93, v233, v93
	s_waitcnt lgkmcnt(0)
	v_mfma_f32_32x32x16_bf16 v[0:15], v[88:91], v[80:83], v[0:15]
	v_cvt_pk_bf16_f32 v80, v133, v135
	v_cvt_pk_bf16_f32 v81, v137, v139
	v_cvt_pk_bf16_f32 v82, v141, v143
	v_cvt_pk_bf16_f32 v83, v239, v241
	v_add_f32_e32 v221, v142, v221
	v_add_f32_e32 v93, v235, v93
	s_waitcnt lgkmcnt(12)
	v_mfma_f32_32x32x16_bf16 v[48:63], v[108:111], v[80:83], v[48:63]
	v_add_f32_e32 v221, v238, v221
	v_add_f32_e32 v93, v237, v93
	v_add_f32_e32 v221, v240, v221
	v_add_f32_e32 v93, v133, v93
	v_add_f32_e32 v93, v135, v93
	s_waitcnt lgkmcnt(6)
	v_mfma_f32_32x32x16_bf16 v[32:47], v[242:245], v[80:83], v[32:47]
	v_add_f32_e32 v93, v137, v93
	v_add_f32_e32 v93, v139, v93
	v_add_f32_e32 v93, v141, v93
	s_waitcnt lgkmcnt(4)
	v_mfma_f32_32x32x16_bf16 v[16:31], v[246:249], v[80:83], v[16:31]
	v_add_f32_e32 v93, v143, v93
	v_add_f32_e32 v93, v239, v93
	s_waitcnt lgkmcnt(2)
	v_mfma_f32_32x32x16_bf16 v[0:15], v[250:253], v[80:83], v[0:15]
	v_add_f32_e32 v93, v241, v93
	v_add_f32_e32 v221, v221, v93
	v_add_f32_e32 v146, v146, v221

; #define LOADV(dst, ks_) do { _Pragma("unroll") for (int dvb = 0; dvb < 4; ++dvb) { dst[2 * dvb] = vtr(vp + dvb * 4096 + (ks_) * 1024); dst[2 * dvb + 1] = vtr(vp + dvb * 4096 + (ks_) * 1024 + 512); } } while (0)
; #define MF4(src, pfrag) do { _Pragma("unroll") for (int dvb = 0; dvb < 4; ++dvb) { \
;         const bf16x8 vf_ = __builtin_shufflevector(src[2 * dvb], src[2 * dvb + 1], 0, 1, 2, 3, 4, 5, 6, 7); o[dvb] = MFMA32(vf_, pfrag, o[dvb]); } } while (0)
; #define EXPQ(S, lo_, RS, PF) do { _Pragma("unroll") for (int i = lo_; i < lo_ + 8; ++i) { S[i] = ex2(S[i]); RS += S[i]; } \
;               u32x4 w_; w_.x = pk2(S[lo_], S[lo_ + 1]); w_.y = pk2(S[lo_ + 2], S[lo_ + 3]); w_.z = pk2(S[lo_ + 4], S[lo_ + 5]); w_.w = pk2(S[lo_ + 6], S[lo_ + 7]); PF = __builtin_bit_cast(bf16x8, w_); } while (0)
; DI void attn_unit(const Params& p, int bh, int qb, char* lds, float lam, int tid, int lane, int wid, const bool build_tab) {
;     ...
;             float rs0 = 0.f, rs1 = 0.f;
;     ...
;             EXPQ(s0, 0, rs0, pf[0]);
;             LOADV(vb, 1);
;             MF4(va, pf[0]);
;             EXPQ(s0, 8, rs1, pf[1]);
;             LOADV(va, 2);
;             MF4(vb, pf[1]);
;             EXPQ(s1, 0, rs0, pf[2]);
;             LOADV(vb, 3);
;             MF4(va, pf[2]);
;             EXPQ(s1, 8, rs1, pf[3]);
;             MF4(vb, pf[3]);
;             l += rs0 + rs1;
.LBB0_379:
	ds_read_b64_tr_b16 v[230:231], v177 offset:21504
	ds_read_b64_tr_b16 v[232:233], v177 offset:22016
	ds_read_b64_tr_b16 v[234:235], v177 offset:25600
	ds_read_b64_tr_b16 v[236:237], v177 offset:26112
	v_exp_f32_e32 v178, v96
	v_exp_f32_e32 v180, v97
	v_exp_f32_e32 v182, v98
	v_exp_f32_e32 v184, v99
	v_exp_f32_e32 v186, v100
	v_exp_f32_e32 v188, v101
	v_exp_f32_e32 v190, v102
	v_exp_f32_e32 v192, v103
	v_cvt_pk_bf16_f32 v96, v178, v180
	v_cvt_pk_bf16_f32 v97, v182, v184
	v_cvt_pk_bf16_f32 v98, v186, v188
	v_cvt_pk_bf16_f32 v99, v190, v192
	ds_read_b64_tr_b16 v[100:101], v177 offset:17408
	ds_read_b64_tr_b16 v[102:103], v177 offset:17920
	s_waitcnt lgkmcnt(12)
	v_mfma_f32_32x32x16_bf16 v[48:63], v[140:143], v[96:99], v[48:63]
	ds_read_b64_tr_b16 v[238:239], v177 offset:29696
	ds_read_b64_tr_b16 v[240:241], v177 offset:30208
	v_exp_f32_e32 v179, v104
	v_exp_f32_e32 v181, v105
	v_exp_f32_e32 v183, v106
	v_add_f32_e32 v242, v180, v178
	s_waitcnt lgkmcnt(12)
	v_mfma_f32_32x32x16_bf16 v[32:47], v[136:139], v[96:99], v[32:47]
	v_exp_f32_e32 v185, v107
	v_exp_f32_e32 v187, v108
	v_exp_f32_e32 v189, v109
	v_add_f32_e32 v242, v182, v242
	s_waitcnt lgkmcnt(10)
	v_mfma_f32_32x32x16_bf16 v[16:31], v[132:135], v[96:99], v[16:31]
	v_exp_f32_e32 v191, v110
	v_exp_f32_e32 v193, v111
	v_add_f32_e32 v242, v184, v242
	v_add_f32_e32 v242, v186, v242
	ds_read_b64_tr_b16 v[104:105], v177 offset:18432
	ds_read_b64_tr_b16 v[106:107], v177 offset:18944
	ds_read_b64_tr_b16 v[108:109], v177 offset:19456
	ds_read_b64_tr_b16 v[110:111], v177 offset:19968
	s_waitcnt lgkmcnt(12)
	v_mfma_f32_32x32x16_bf16 v[0:15], v[128:131], v[96:99], v[0:15]
	ds_read_b64_tr_b16 v[128:129], v177 offset:26624
	ds_read_b64_tr_b16 v[130:131], v177 offset:27136
	v_cvt_pk_bf16_f32 v96, v179, v181
	v_cvt_pk_bf16_f32 v97, v183, v185
	v_cvt_pk_bf16_f32 v98, v187, v189
	v_cvt_pk_bf16_f32 v99, v191, v193
	v_exp_f32_e32 v140, v84
	v_exp_f32_e32 v142, v85
	s_waitcnt lgkmcnt(8)
	v_mfma_f32_32x32x16_bf16 v[48:63], v[100:103], v[96:99], v[48:63]
	v_exp_f32_e32 v194, v86
	v_exp_f32_e32 v196, v87
	v_add_f32_e32 v242, v188, v242
	ds_read_b64_tr_b16 v[84:85], v177 offset:22528
	ds_read_b64_tr_b16 v[86:87], v177 offset:23040
	v_exp_f32_e32 v136, v82
	s_waitcnt lgkmcnt(14)
	v_mfma_f32_32x32x16_bf16 v[32:47], v[230:233], v[96:99], v[32:47]
	ds_read_b64_tr_b16 v[230:231], v177 offset:23552
	ds_read_b64_tr_b16 v[232:233], v177 offset:24064
	v_exp_f32_e32 v138, v83
	v_exp_f32_e32 v132, v80
	v_exp_f32_e32 v134, v81
	v_add_f32_e32 v242, v190, v242
	s_waitcnt lgkmcnt(14)
	v_mfma_f32_32x32x16_bf16 v[16:31], v[234:237], v[96:99], v[16:31]
	ds_read_b64_tr_b16 v[234:235], v177 offset:27648
	ds_read_b64_tr_b16 v[236:237], v177 offset:28160
	v_cvt_pk_bf16_f32 v80, v132, v134
	v_cvt_pk_bf16_f32 v81, v136, v138
	v_cvt_pk_bf16_f32 v82, v140, v142
	v_cvt_pk_bf16_f32 v83, v194, v196
	v_exp_f32_e32 v133, v88
	v_exp_f32_e32 v135, v89
	s_waitcnt lgkmcnt(12)
	v_mfma_f32_32x32x16_bf16 v[0:15], v[238:241], v[96:99], v[0:15]
	ds_read_b64_tr_b16 v[238:239], v177 offset:31744
	ds_read_b64_tr_b16 v[240:241], v177 offset:32256
	v_exp_f32_e32 v137, v90
	v_exp_f32_e32 v139, v91
	v_add_f32_e32 v242, v192, v242
	ds_read_b64_tr_b16 v[88:89], v177 offset:30720
	ds_read_b64_tr_b16 v[90:91], v177 offset:31232
	v_exp_f32_e32 v141, v92
	s_waitcnt lgkmcnt(14)
	v_mfma_f32_32x32x16_bf16 v[48:63], v[104:107], v[80:83], v[48:63]
	v_exp_f32_e32 v143, v93
	v_exp_f32_e32 v195, v94
	v_exp_f32_e32 v197, v95
	v_add_f32_e32 v242, v132, v242
	s_waitcnt lgkmcnt(8)
	v_mfma_f32_32x32x16_bf16 v[32:47], v[84:87], v[80:83], v[32:47]
	v_add_f32_e32 v243, v181, v179
	v_add_f32_e32 v242, v134, v242
	v_add_f32_e32 v243, v183, v243
	v_add_f32_e32 v242, v136, v242
	s_waitcnt lgkmcnt(10)
	v_mfma_f32_32x32x16_bf16 v[16:31], v[128:131], v[80:83], v[16:31]
	v_add_f32_e32 v243, v185, v243
	v_add_f32_e32 v242, v138, v242
	v_add_f32_e32 v243, v187, v243
	v_add_f32_e32 v242, v140, v242
	v_add_f32_e32 v243, v189, v243
	s_waitcnt lgkmcnt(0)
	v_mfma_f32_32x32x16_bf16 v[0:15], v[88:91], v[80:83], v[0:15]
	v_cvt_pk_bf16_f32 v80, v133, v135
	v_cvt_pk_bf16_f32 v81, v137, v139
	v_cvt_pk_bf16_f32 v82, v141, v143
	v_cvt_pk_bf16_f32 v83, v195, v197
	v_add_f32_e32 v242, v142, v242
	v_add_f32_e32 v243, v191, v243
	s_waitcnt lgkmcnt(12)
	v_mfma_f32_32x32x16_bf16 v[48:63], v[108:111], v[80:83], v[48:63]
	v_add_f32_e32 v242, v194, v242
	v_add_f32_e32 v243, v193, v243
	v_add_f32_e32 v242, v196, v242
	v_add_f32_e32 v243, v133, v243
	v_add_f32_e32 v243, v135, v243
	s_waitcnt lgkmcnt(6)
	v_mfma_f32_32x32x16_bf16 v[32:47], v[230:233], v[80:83], v[32:47]
	v_add_f32_e32 v243, v137, v243
	v_add_f32_e32 v243, v139, v243
	v_add_f32_e32 v243, v141, v243
	s_waitcnt lgkmcnt(4)
	v_mfma_f32_32x32x16_bf16 v[16:31], v[234:237], v[80:83], v[16:31]
	v_add_f32_e32 v243, v143, v243
	v_add_f32_e32 v243, v195, v243
	s_waitcnt lgkmcnt(2)
	v_mfma_f32_32x32x16_bf16 v[0:15], v[238:241], v[80:83], v[0:15]
	v_add_f32_e32 v243, v197, v243
	v_add_f32_e32 v242, v242, v243
	v_add_f32_e32 v176, v176, v242
